# v27
# speedup vs baseline: 1.0077x; 1.0077x over previous
; __device__ __forceinline__ void convert_matrix(const Ctx& C, const float* W, int K, int N, bf16* WT, int mode, const float* gs) {
;     ...
;     for (int it = gw; it < nitems; it += NGW) {
;         const int kb = it / nblk, nb = it % nblk, n0 = nb * 32;
;         int drow0 = n0;
;         if (mode == 1) { const int j = n0 < DFF ? n0 : n0 - DFF; drow0 = 256 * (j >> 7) + (j & 127) + (n0 < DFF ? 0 : 128); }
;         transpose_item(W, K, N, WT, kb * 64, n0, drow0, scr, C.lane, gs, mode);
;     }
; }
; __device__ __forceinline__ void convert_layer(const Ctx& C, int li) {
;     unsigned char* wl = C.ws + WS_W + (size_t)li * WL_SIZE;
;     convert_matrix(C, C.in[3] + (size_t)li * D * NPROJ, D, NPROJ, (bf16*)(wl + WL_IN), 2, C.in[2] + (size_t)li * D);
;     convert_matrix(C, C.in[13] + (size_t)li * D * D, D, D, (bf16*)(wl + WL_OUT), 0, nullptr);
;     convert_matrix(C, C.in[15] + (size_t)li * D * 2 * DFF, D, 2 * DFF, (bf16*)(wl + WL_UP), 1, C.in[14] + (size_t)li * D);
;     convert_matrix(C, C.in[18] + (size_t)li * DFF * D, DFF, D, (bf16*)(wl + WL_DOWN), 0, nullptr);
;     convert_matrix(C, C.in[20] + (size_t)li * D * D, D, D, (bf16*)(wl + WL_GATE), 0, C.in[19] + (size_t)li * D);
;     convert_matrix(C, C.in[21] + (size_t)li * PLE * D, PLE, D, (bf16*)(wl + WL_PROJ), 0, nullptr);
.Lp0_loop:
	s_add_u32 s59, s58, s44
	s_cmp_lt_u32 s59, 34624
	s_cbranch_scc0 .Lp0_nonext
	s_mov_b32 s6, s59
	s_mov_b32 s7, 0
	s_cmp_lt_u32 s59, 26912
	s_cbranch_scc1 .Lp0_lay0_b
	s_sub_u32 s6, s59, 26912
	s_mov_b32 s7, 1

; __device__ __forceinline__ f32x4 mma16(bf16x8 x2, bf16x8 x1, f32x4 acc) { return __builtin_amdgcn_mfma_f32_16x16x32_bf16(x2, x1, acc, 0, 0, 0); }
; __device__ __forceinline__ void skinny_proj(const Ctx& C, const bf16* X, const bf16* Wt, const float* SS, bf16* PROJ) {
;     ...
; #pragma unroll 8
;     for (int ks = 0; ks < D / 32; ++ks) {
;         const bf16x8 a = *(const bf16x8*)(A + ks * 32), b0 = *(const bf16x8*)(W0 + ks * 32), b1 = *(const bf16x8*)(W0 + (size_t)16 * D + ks * 32);
;         acc0 = mma16(b0, a, acc0); acc1 = mma16(b1, a, acc1);
;     }
.LBB0_1411:
	v_lshl_add_u64 v[28:29], v[12:13], 0, s[12:13]
	v_add_co_u32_e32 v48, vcc, 0x8000000, v28
	v_lshl_add_u64 v[44:45], v[10:11], 0, s[12:13]
	s_nop 0
	v_addc_co_u32_e32 v49, vcc, 0, v29, vcc
	global_load_dwordx4 v[16:19], v[44:45], off
	global_load_dwordx4 v[20:23], v[44:45], off offset:64
	global_load_dwordx4 v[24:27], v[48:49], off
	v_add_co_u32_e32 v50, vcc, 0x8010000, v28
	s_add_u32 s12, s12, 0x200
	s_nop 0
	v_addc_co_u32_e32 v51, vcc, 0, v29, vcc
	global_load_dwordx4 v[28:31], v[48:49], off offset:64
	global_load_dwordx4 v[32:35], v[50:51], off
	s_addc_u32 s13, s13, 0
	s_cmpk_lg_i32 s12, 0x1000
	s_waitcnt vmcnt(0)
	v_mfma_f32_16x16x32_bf16 v[4:7], v[32:35], v[16:19], v[4:7]
	v_mfma_f32_16x16x32_bf16 v[0:3], v[24:27], v[16:19], v[0:3]
	global_load_dwordx4 v[24:27], v[50:51], off offset:64
	global_load_dwordx4 v[16:19], v[44:45], off offset:128
	global_load_dwordx4 v[32:35], v[44:45], off offset:192
	global_load_dwordx4 v[36:39], v[44:45], off offset:256
	v_mfma_f32_16x16x32_bf16 v[0:3], v[28:31], v[20:23], v[0:3]
	global_load_dwordx4 v[28:31], v[48:49], off offset:128
	global_load_dwordx4 v[40:43], v[48:49], off offset:192
	s_waitcnt vmcnt(1)
	v_mfma_f32_16x16x32_bf16 v[0:3], v[28:31], v[16:19], v[0:3]
	v_mfma_f32_16x16x32_bf16 v[4:7], v[24:27], v[20:23], v[4:7]
	global_load_dwordx4 v[20:23], v[50:51], off offset:128
	global_load_dwordx4 v[24:27], v[50:51], off offset:192
	s_waitcnt vmcnt(2)
	v_mfma_f32_16x16x32_bf16 v[0:3], v[40:43], v[32:35], v[0:3]
	s_waitcnt vmcnt(1)
	v_mfma_f32_16x16x32_bf16 v[4:7], v[20:23], v[16:19], v[4:7]
	global_load_dwordx4 v[16:19], v[44:45], off offset:320
	global_load_dwordx4 v[20:23], v[44:45], off offset:384
	global_load_dwordx4 v[28:31], v[44:45], off offset:448
	global_load_dwordx4 v[40:43], v[48:49], off offset:256
	s_nop 0
	global_load_dwordx4 v[44:47], v[48:49], off offset:320
	s_waitcnt vmcnt(5)
	v_mfma_f32_16x16x32_bf16 v[4:7], v[24:27], v[32:35], v[4:7]
	global_load_dwordx4 v[24:27], v[50:51], off offset:256
	global_load_dwordx4 v[32:35], v[50:51], off offset:320
	s_waitcnt vmcnt(3)
	v_mfma_f32_16x16x32_bf16 v[0:3], v[40:43], v[36:39], v[0:3]
	s_waitcnt vmcnt(1)
	v_mfma_f32_16x16x32_bf16 v[4:7], v[24:27], v[36:39], v[4:7]
	global_load_dwordx4 v[24:27], v[48:49], off offset:384
	global_load_dwordx4 v[36:39], v[50:51], off offset:384
	v_mfma_f32_16x16x32_bf16 v[0:3], v[44:47], v[16:19], v[0:3]
	s_waitcnt vmcnt(2)
	v_mfma_f32_16x16x32_bf16 v[4:7], v[32:35], v[16:19], v[4:7]
	global_load_dwordx4 v[16:19], v[48:49], off offset:448
	s_waitcnt vmcnt(2)
	v_mfma_f32_16x16x32_bf16 v[0:3], v[24:27], v[20:23], v[0:3]
	global_load_dwordx4 v[24:27], v[50:51], off offset:448
	s_waitcnt vmcnt(2)
	v_mfma_f32_16x16x32_bf16 v[4:7], v[36:39], v[20:23], v[4:7]
	s_waitcnt vmcnt(1)
	v_mfma_f32_16x16x32_bf16 v[0:3], v[16:19], v[28:31], v[0:3]
	s_waitcnt vmcnt(0)
	v_mfma_f32_16x16x32_bf16 v[4:7], v[24:27], v[28:31], v[4:7]
	s_cbranch_scc1 .LBB0_1411
; #define LAS __attribute__((address_space(3)))
; __device__ __forceinline__ unsigned pk2(float lo, float hi) { return pg8::cvt_pk_bf16(lo, hi); }
; __device__ __forceinline__ void convert_matrix(const Ctx& C, const float* W, int K, int N, bf16* WT, int mode, const float* gs) {
;     LAS float* scr = (LAS float*)(C.lds + C.wave * 16384);
;     const int gw = C.bid * 8 + C.wave, NGW = C.G * 8;
;     const int nblk = N / 32, nitems = (K / 64) * nblk;
;     for (int it = gw; it < nitems; it += NGW) {
;         const int kb = it / nblk, nb = it % nblk, n0 = nb * 32;
;         int drow0 = n0;
;         if (mode == 1) { const int j = n0 < DFF ? n0 : n0 - DFF; drow0 = 256 * (j >> 7) + (j & 127) + (n0 < DFF ? 0 : 128); }
;         transpose_item(W, K, N, WT, kb * 64, n0, drow0, scr, C.lane, gs, mode);
; __device__ __forceinline__ void skinny_proj(const Ctx& C, const bf16* X, const bf16* Wt, const float* SS, bf16* PROJ) {
;     ...
;     const f32x4* p = (const f32x4*)(SS + (size_t)(r0 + fr) * 32); f32x4 sa = p[0];
; #pragma unroll
;     for (int q = 1; q < 8; ++q) sa = sa + p[q];
;     const float rs = rsqrtf(((sa[0] + sa[1]) + (sa[2] + sa[3])) * (1.0f / D) + EPS);
;     bf16* o = PROJ + (size_t)(r0 + fr) * LDP + NMAIN + 4 * fq;
;     *(v2u*)o = (v2u){pk2(acc0[0] * rs, acc0[1] * rs), pk2(acc0[2] * rs, acc0[3] * rs)};
;     *(v2u*)(o + 16) = (v2u){pk2(acc1[0] * rs, acc1[1] * rs), pk2(acc1[2] * rs, acc1[3] * rs)};
	v_lshlrev_b64 v[10:11], 7, v[8:9]
	v_lshl_add_u64 v[44:45], s[20:21], 0, v[10:11]
	global_load_dwordx4 v[10:13], v[44:45], off
	global_load_dwordx4 v[16:19], v[44:45], off offset:16
	global_load_dwordx4 v[20:23], v[44:45], off offset:32
	global_load_dwordx4 v[24:27], v[44:45], off offset:48
	global_load_dwordx4 v[28:31], v[44:45], off offset:64
	global_load_dwordx4 v[32:35], v[44:45], off offset:80
	global_load_dwordx4 v[36:39], v[44:45], off offset:96
	global_load_dwordx4 v[40:43], v[44:45], off offset:112
	v_mov_b32_e32 v46, 0x358637bd
	s_movk_i32 s12, 0x2e00
	v_mov_b64_e32 v[44:45], s[16:17]
	s_mov_b32 s14, 0x800000
	v_mad_i64_i32 v[8:9], s[12:13], v8, s12, v[44:45]
	v_lshlrev_b32_e32 v14, 3, v14
	v_mov_b32_e32 v15, 0
	s_mov_b64 s[10:11], 0x2c00
	s_movk_i32 s15, 0x2000
	v_lshl_add_u64 v[8:9], v[8:9], 0, v[14:15]
	v_lshl_add_u64 v[14:15], v[8:9], 0, s[10:11]
	v_add_co_u32_e32 v8, vcc, s15, v8
	s_waitcnt vmcnt(6)
	v_pk_add_f32 v[12:13], v[12:13], v[18:19]
	v_pk_add_f32 v[10:11], v[10:11], v[16:17]
	s_waitcnt vmcnt(5)
	v_pk_add_f32 v[12:13], v[12:13], v[22:23]
	v_pk_add_f32 v[10:11], v[10:11], v[20:21]
	s_waitcnt vmcnt(4)
	v_pk_add_f32 v[12:13], v[12:13], v[26:27]
	v_pk_add_f32 v[10:11], v[10:11], v[24:25]
	s_waitcnt vmcnt(3)
	v_pk_add_f32 v[12:13], v[12:13], v[30:31]
	v_pk_add_f32 v[10:11], v[10:11], v[28:29]
	s_waitcnt vmcnt(2)
	v_pk_add_f32 v[12:13], v[12:13], v[34:35]
	v_pk_add_f32 v[10:11], v[10:11], v[32:33]
	s_waitcnt vmcnt(1)
	v_pk_add_f32 v[12:13], v[12:13], v[38:39]
	v_pk_add_f32 v[10:11], v[10:11], v[36:37]
	s_waitcnt vmcnt(0)
	v_pk_add_f32 v[12:13], v[12:13], v[42:43]
	v_pk_add_f32 v[10:11], v[10:11], v[40:41]
	v_addc_co_u32_e32 v9, vcc, 0, v9, vcc
	v_pk_mov_b32 v[16:17], v[10:11], v[12:13] op_sel:[1,0]
	v_mov_b32_e32 v11, v13
	v_pk_add_f32 v[10:11], v[16:17], v[10:11]
	s_nop 0
	v_add_f32_e32 v10, v10, v11
	v_fmac_f32_e32 v46, 0x3a000000, v10
	v_mul_f32_e32 v10, 0x4b800000, v46
	v_cmp_gt_f32_e64 s[12:13], s14, v46
	s_nop 1
	v_cndmask_b32_e64 v10, v46, v10, s[12:13]
	v_rsq_f32_e32 v10, v10
	s_nop 0
	v_mul_f32_e32 v11, 0x45800000, v10
	v_cndmask_b32_e64 v10, v10, v11, s[12:13]
	v_pk_mul_f32 v[0:1], v[0:1], v[10:11] op_sel_hi:[1,0]
	v_pk_mul_f32 v[2:3], v[2:3], v[10:11] op_sel_hi:[1,0]
	v_pk_mul_f32 v[4:5], v[4:5], v[10:11] op_sel_hi:[1,0]
	v_pk_mul_f32 v[6:7], v[6:7], v[10:11] op_sel_hi:[1,0]
	v_cvt_pk_bf16_f32 v0, v0, v1
	v_cvt_pk_bf16_f32 v1, v2, v3
	v_cvt_pk_bf16_f32 v2, v4, v5
	v_cvt_pk_bf16_f32 v3, v6, v7
	global_store_dwordx2 v[8:9], v[0:1], off offset:3072
	global_store_dwordx2 v[14:15], v[2:3], off offset:32
	v_writelane_b32 v250, s6, 0
	v_writelane_b32 v250, s7, 1
	v_writelane_b32 v250, s8, 2
	v_writelane_b32 v250, s9, 3
	v_writelane_b32 v250, s10, 4
	v_writelane_b32 v250, s11, 5
	v_writelane_b32 v250, s12, 6
	v_writelane_b32 v250, s13, 7
	v_writelane_b32 v250, s14, 8
	v_writelane_b32 v250, s15, 9
	v_writelane_b32 v250, s16, 10
	v_writelane_b32 v250, s17, 11
	v_writelane_b32 v250, s18, 12
	v_writelane_b32 v250, s19, 13
	v_writelane_b32 v250, s20, 14
	v_writelane_b32 v250, s21, 15
	v_writelane_b32 v250, s22, 16
	v_writelane_b32 v250, s23, 17
	v_writelane_b32 v250, s24, 18
	v_writelane_b32 v250, s25, 19
	v_writelane_b32 v250, s26, 20
	v_writelane_b32 v250, s27, 21
	v_writelane_b32 v250, s28, 22
	v_writelane_b32 v250, s29, 23
	v_writelane_b32 v250, s30, 24
	v_writelane_b32 v250, s31, 25
	v_writelane_b32 v250, s32, 26
	v_writelane_b32 v250, s33, 27
	v_writelane_b32 v250, s34, 28
	v_writelane_b32 v250, s35, 29
	v_writelane_b32 v250, s36, 30
	v_writelane_b32 v250, s37, 31
	v_writelane_b32 v250, s38, 32
	v_writelane_b32 v250, s39, 33
	v_writelane_b32 v250, s40, 34
	v_writelane_b32 v250, s41, 35
	v_writelane_b32 v250, s42, 36
	v_writelane_b32 v250, s43, 37
	v_writelane_b32 v250, s44, 38
	v_writelane_b32 v250, s45, 39
	v_writelane_b32 v250, s46, 40
	v_writelane_b32 v250, s47, 41
	v_writelane_b32 v250, s48, 42
	v_writelane_b32 v250, s49, 43
	v_writelane_b32 v250, s50, 44
	v_writelane_b32 v250, s51, 45
	v_writelane_b32 v250, s52, 46
	v_writelane_b32 v250, s53, 47
	v_writelane_b32 v250, s54, 48
	v_writelane_b32 v250, s55, 49
	v_writelane_b32 v250, s56, 50
	v_writelane_b32 v250, s57, 51
	v_writelane_b32 v250, s58, 52
	v_writelane_b32 v250, s59, 53
	v_writelane_b32 v250, s60, 54
	v_writelane_b32 v250, s61, 55
	v_writelane_b32 v250, s62, 56
	v_writelane_b32 v250, s63, 57
	v_writelane_b32 v250, s64, 58
	v_writelane_b32 v250, s65, 59
	v_writelane_b32 v250, s66, 60
	v_writelane_b32 v250, s67, 61
	v_writelane_b32 v250, s68, 62
	v_writelane_b32 v250, s69, 63
	v_writelane_b32 v251, s70, 0
	v_writelane_b32 v251, s71, 1
	v_writelane_b32 v251, s72, 2
	v_writelane_b32 v251, s73, 3
	v_writelane_b32 v251, s74, 4
	v_writelane_b32 v251, s75, 5
	v_writelane_b32 v251, s76, 6
	v_writelane_b32 v251, s77, 7
	v_writelane_b32 v251, s78, 8
	v_writelane_b32 v251, s79, 9
	s_load_dwordx4 s[24:27], s[0:1], 0x10
	s_load_dwordx2 s[28:29], s[0:1], 0x68
	s_load_dwordx4 s[36:39], s[0:1], 0x70
	s_load_dwordx2 s[30:31], s[0:1], 0x90
	s_load_dwordx4 s[40:43], s[0:1], 0x98
	s_load_dwordx2 s[34:35], s[0:1], 0xa8
	s_load_dwordx2 s[48:49], s[0:1], 0xc0
	s_load_dwordx4 s[64:67], s[0:1], 0x0
	v_readfirstlane_b32 s78, v234
	s_lshr_b32 s78, s78, 6
	s_sub_u32 s58, s2, 128
	s_lshl_b32 s58, s58, 3
	s_add_u32 s58, s58, s78
	s_add_u32 s58, s58, 34624
	s_lshl_b32 s78, s78, 14
	v_and_b32_e32 v1, 63, v234
	v_lshrrev_b32_e32 v6, 5, v1
	v_and_b32_e32 v7, 31, v1
	v_lshlrev_b32_e32 v7, 2, v7
	v_mul_u32_u24_e32 v2, 0x84, v6
	v_add3_u32 v2, s78, v2, v7
	v_and_b32_e32 v4, 7, v1
	v_lshrrev_b32_e32 v8, 3, v1
	v_mul_u32_u24_e32 v3, 0x420, v4
	v_lshlrev_b32_e32 v108, 2, v8
	v_add3_u32 v3, s78, v3, v108
	v_lshlrev_b32_e32 v5, 5, v4
	v_lshlrev_b32_e32 v4, 4, v4
	v_mov_b32_e32 v10, 0
	s_waitcnt lgkmcnt(0)
	s_mov_b32 s6, s58
	s_mov_b32 s7, 0
	s_cmp_lt_u32 s58, 26912
	s_cbranch_scc1 .Lr0_lay0_a
	s_sub_u32 s6, s58, 26912
	s_mov_b32 s7, 1

; #define LAS __attribute__((address_space(3)))
; __device__ __forceinline__ unsigned pk2(float lo, float hi) { return pg8::cvt_pk_bf16(lo, hi); }
;     ...
;     for (int j = 0; j < 4; ++j) { const int n = (lane >> 3) + 8 * j; const LAS float* s = scr + (8 * c) * 33 + n;
;         v4u o; o.x = pk2(s[0 * 33], s[1 * 33]); o.y = pk2(s[2 * 33], s[3 * 33]); o.z = pk2(s[4 * 33], s[5 * 33]); o.w = pk2(s[6 * 33], s[7 * 33]);
;         const int drow = mode == 2 ? inproj_col(n0 + n) : drow0 + n;
;         *(v4u*)(WT + (size_t)drow * K + k0 + 8 * c) = o; }
; __device__ __forceinline__ void xcd_barrier(const XcdBarrier& b) {
;     asm volatile("s_waitcnt vmcnt(0)" ::: "memory");
;     __syncthreads();
;     if (threadIdx.x == 0) {
;         unsigned* bar = b.bar;
;         __builtin_amdgcn_s_waitcnt(0);
;         unsigned nloc = b.st[0], nx = b.st[1];
;         if (nloc == 0u) { xcd_barrier_complete(bar, b.x, nloc, nx); b.st[0] = nloc; b.st[1] = nx; }
.Lr0_havegs:
	s_waitcnt lgkmcnt(12)
	v_pk_mul_f32 v[52:53], v[52:53], v[12:13]
	v_pk_mul_f32 v[54:55], v[54:55], v[14:15]
	v_pk_mul_f32 v[56:57], v[56:57], v[16:17]
	v_pk_mul_f32 v[58:59], v[58:59], v[18:19]
	v_cvt_pk_bf16_f32 v84, v52, v53
	v_cvt_pk_bf16_f32 v85, v54, v55
	v_cvt_pk_bf16_f32 v86, v56, v57
	v_cvt_pk_bf16_f32 v87, v58, v59
	global_store_dwordx4 v100, v[84:87], s[50:51] sc0 sc1
	s_waitcnt lgkmcnt(8)
	v_pk_mul_f32 v[60:61], v[60:61], v[12:13]
	v_pk_mul_f32 v[62:63], v[62:63], v[14:15]
	v_pk_mul_f32 v[64:65], v[64:65], v[16:17]
	v_pk_mul_f32 v[66:67], v[66:67], v[18:19]
	v_cvt_pk_bf16_f32 v88, v60, v61
	v_cvt_pk_bf16_f32 v89, v62, v63
	v_cvt_pk_bf16_f32 v90, v64, v65
	v_cvt_pk_bf16_f32 v91, v66, v67
	global_store_dwordx4 v101, v[88:91], s[50:51] sc0 sc1
	s_waitcnt lgkmcnt(4)
	v_pk_mul_f32 v[68:69], v[68:69], v[12:13]
	v_pk_mul_f32 v[70:71], v[70:71], v[14:15]
	v_pk_mul_f32 v[72:73], v[72:73], v[16:17]
	v_pk_mul_f32 v[74:75], v[74:75], v[18:19]
	v_cvt_pk_bf16_f32 v92, v68, v69
	v_cvt_pk_bf16_f32 v93, v70, v71
	v_cvt_pk_bf16_f32 v94, v72, v73
	v_cvt_pk_bf16_f32 v95, v74, v75
	global_store_dwordx4 v102, v[92:95], s[50:51] sc0 sc1
	s_waitcnt lgkmcnt(0)
	v_pk_mul_f32 v[76:77], v[76:77], v[12:13]
	v_pk_mul_f32 v[78:79], v[78:79], v[14:15]
	v_pk_mul_f32 v[80:81], v[80:81], v[16:17]
	v_pk_mul_f32 v[82:83], v[82:83], v[18:19]
	v_cvt_pk_bf16_f32 v96, v76, v77
	v_cvt_pk_bf16_f32 v97, v78, v79
	v_cvt_pk_bf16_f32 v98, v80, v81
	v_cvt_pk_bf16_f32 v99, v82, v83
	global_store_dwordx4 v103, v[96:99], s[50:51] sc0 sc1
	s_mov_b32 s50, s70
	s_mov_b32 s51, s71
	s_mov_b32 s52, s72
	s_mov_b32 s53, s73
	s_mov_b32 s54, s74
	s_mov_b32 s55, s75
	s_mov_b32 s56, s76
	s_mov_b32 s57, s77
	s_mov_b32 s58, s59
	s_cmp_eq_u32 s63, 1
	s_cbranch_scc1 .Lr0_loop
	s_waitcnt vmcnt(0)
	v_readlane_b32 s6, v250, 0
	v_readlane_b32 s7, v250, 1
	v_readlane_b32 s8, v250, 2
	v_readlane_b32 s9, v250, 3
	v_readlane_b32 s10, v250, 4
	v_readlane_b32 s11, v250, 5
	v_readlane_b32 s12, v250, 6
	v_readlane_b32 s13, v250, 7
	v_readlane_b32 s14, v250, 8
	v_readlane_b32 s15, v250, 9
	v_readlane_b32 s16, v250, 10
	v_readlane_b32 s17, v250, 11
	v_readlane_b32 s18, v250, 12
	v_readlane_b32 s19, v250, 13
	v_readlane_b32 s20, v250, 14
	v_readlane_b32 s21, v250, 15
	v_readlane_b32 s22, v250, 16
	v_readlane_b32 s23, v250, 17
	v_readlane_b32 s24, v250, 18
	v_readlane_b32 s25, v250, 19
	v_readlane_b32 s26, v250, 20
	v_readlane_b32 s27, v250, 21
	v_readlane_b32 s28, v250, 22
	v_readlane_b32 s29, v250, 23
	v_readlane_b32 s30, v250, 24
	v_readlane_b32 s31, v250, 25
	v_readlane_b32 s32, v250, 26
	v_readlane_b32 s33, v250, 27
	v_readlane_b32 s34, v250, 28
	v_readlane_b32 s35, v250, 29
	v_readlane_b32 s36, v250, 30
	v_readlane_b32 s37, v250, 31
	v_readlane_b32 s38, v250, 32
	v_readlane_b32 s39, v250, 33
	v_readlane_b32 s40, v250, 34
	v_readlane_b32 s41, v250, 35
	v_readlane_b32 s42, v250, 36
	v_readlane_b32 s43, v250, 37
	v_readlane_b32 s44, v250, 38
	v_readlane_b32 s45, v250, 39
	v_readlane_b32 s46, v250, 40
	v_readlane_b32 s47, v250, 41
	v_readlane_b32 s48, v250, 42
	v_readlane_b32 s49, v250, 43
	v_readlane_b32 s50, v250, 44
	v_readlane_b32 s51, v250, 45
	v_readlane_b32 s52, v250, 46
	v_readlane_b32 s53, v250, 47
	v_readlane_b32 s54, v250, 48
	v_readlane_b32 s55, v250, 49
	v_readlane_b32 s56, v250, 50
	v_readlane_b32 s57, v250, 51
	v_readlane_b32 s58, v250, 52
	v_readlane_b32 s59, v250, 53
	v_readlane_b32 s60, v250, 54
	v_readlane_b32 s61, v250, 55
	v_readlane_b32 s62, v250, 56
	v_readlane_b32 s63, v250, 57
	v_readlane_b32 s64, v250, 58
	v_readlane_b32 s65, v250, 59
	v_readlane_b32 s66, v250, 60
	v_readlane_b32 s67, v250, 61
	v_readlane_b32 s68, v250, 62
	v_readlane_b32 s69, v250, 63
	v_readlane_b32 s70, v251, 0
	v_readlane_b32 s71, v251, 1
	v_readlane_b32 s72, v251, 2
	v_readlane_b32 s73, v251, 3
	v_readlane_b32 s74, v251, 4
	v_readlane_b32 s75, v251, 5
	v_readlane_b32 s76, v251, 6
	v_readlane_b32 s77, v251, 7
	v_readlane_b32 s78, v251, 8
	v_readlane_b32 s79, v251, 9
.LBB0_1413:
	s_mov_b32 s16, 0
	s_getreg_b32 s10, hwreg(HW_REG_XCC_ID, 0, 4)
	s_waitcnt vmcnt(0)
	s_waitcnt vmcnt(0)
	s_barrier
	s_and_saveexec_b64 s[12:13], s[4:5]
	s_cbranch_execz .LBB0_1465
	v_writelane_b32 v16, s14, 0
	v_writelane_b32 v16, s15, 1
	v_writelane_b32 v16, s16, 2
	v_writelane_b32 v16, s17, 3
	v_writelane_b32 v16, s18, 4
	v_writelane_b32 v16, s19, 5
	v_writelane_b32 v16, s20, 6
	v_writelane_b32 v16, s21, 7
	v_writelane_b32 v16, s22, 8
	v_writelane_b32 v16, s23, 9
	v_writelane_b32 v16, s24, 10
	v_writelane_b32 v16, s25, 11
	v_mov_b32_e32 v10, 0x23f08
	ds_read_b32 v11, v10
	s_load_dwordx2 s[14:15], s[0:1], 0xc0
	s_waitcnt lgkmcnt(0)
	v_readfirstlane_b32 s16, v11
	s_cmp_eq_u32 s16, 1
	s_cbranch_scc1 .Llb_go_11
	s_cmp_eq_u32 s16, 2
	s_cbranch_scc1 .Llb_full_11
	s_mov_b64 s[18:19], exec
	s_mov_b64 exec, -1
	s_add_u32 s20, s14, 0x25d04000
	s_addc_u32 s21, s15, 0
	v_and_b32_e32 v2, 63, v234
	v_lshlrev_b32_e32 v3, 2, v2
	v_and_b32_e32 v9, 7, v2
	v_lshlrev_b32_e32 v9, 2, v9
	global_load_dword v4, v3, s[20:21] sc1
	global_load_dword v5, v3, s[20:21] offset:256 sc1
	global_load_dword v6, v3, s[20:21] offset:512 sc1
	global_load_dword v7, v3, s[20:21] offset:768 sc1
	global_load_dword v8, v9, s[20:21] sc1
	s_waitcnt vmcnt(0)
	v_cmp_eq_u32_e32 vcc, v4, v8
	s_mov_b64 s[24:25], vcc
	v_cmp_eq_u32_e32 vcc, v5, v8
	s_and_b64 s[24:25], s[24:25], vcc
	v_cmp_eq_u32_e32 vcc, v6, v8
	s_and_b64 s[24:25], s[24:25], vcc
	v_cmp_eq_u32_e32 vcc, v7, v8
	s_and_b64 s[24:25], s[24:25], vcc
	v_cmp_ne_u32_e32 vcc, 0, v8
	s_and_b64 s[24:25], s[24:25], vcc
	s_mov_b32 s16, 2
	s_cmp_eq_u64 s[24:25], exec
	s_cbranch_scc0 .Llb_dec_11
	s_cmpk_eq_i32 s46, 0x100
	s_cbranch_scc0 .Llb_dec_11
	s_mov_b32 s16, 1
